# speedup vs baseline: 1.0161x; 1.0066x over previous
; #define SBAR() __builtin_amdgcn_sched_barrier(0)
; __device__ __forceinline__ void qkt8(f32x16& p0, f32x16& p1, const char* Ks, const i32x8* q8, int r32, int hi) {
;     const int s127 = 127, s124 = 124;
;     const int sw0 = (r32 >> 1) & 7, sw1 = ((32 + r32) >> 1) & 7; const char* rp0 = Ks + r32 * 128; const char* rp1 = Ks + (32 + r32) * 128;
;     ...
;     {   i32x8 ka = K8LD(rp0, 0, sw0), kb = K8LD(rp1, 0, sw1);
;         asm volatile("s_waitcnt lgkmcnt(0)" ::: "memory");
;         asm volatile("v_mfma_scale_f32_32x32x64_f8f6f4 %0, %1, %2, -4.0, %3, %4 op_sel_hi:[0,0,0]" : "=&v"(p0) : "v"(ka), "v"(q8[0]), "v"(s127), "v"(s124));
;         asm volatile("v_mfma_scale_f32_32x32x64_f8f6f4 %0, %1, %2, -4.0, %3, %4 op_sel_hi:[0,0,0]" : "=&v"(p1) : "v"(kb), "v"(q8[0]), "v"(s127), "v"(s124)); }
;     {   i32x8 ka = K8LD(rp0, 1, sw0), kb = K8LD(rp1, 1, sw1);
;         asm volatile("s_waitcnt lgkmcnt(0)" ::: "memory");
;         asm volatile("v_mfma_scale_f32_32x32x64_f8f6f4 %0, %1, %2, %0, %3, %4 op_sel_hi:[0,0,0]" : "+v"(p0) : "v"(ka), "v"(q8[1]), "v"(s127), "v"(s124));
;         asm volatile("v_mfma_scale_f32_32x32x64_f8f6f4 %0, %1, %2, %0, %3, %4 op_sel_hi:[0,0,0]" : "+v"(p1) : "v"(kb), "v"(q8[1]), "v"(s127), "v"(s124)); }
; }
; __device__ __forceinline__ void finishSM8(f32x16& p0, f32x16& p1, float& l_reg, i32x8& pa) {
;     for (int r = 0; r < 16; ++r) p1[r] = __builtin_amdgcn_exp2f(p1[r]);
;     float ps = 0; for (int r = 0; r < 16; ++r) ps += p0[r]; for (int r = 0; r < 16; ++r) ps += p1[r];
;     l_reg += ps;
; #pragma unroll
; template <bool FIXED> ...
;     ...
;     for (int j = 1; j + 1 < NT; j += 2) {
;         SBAR(); QKT(pB0, pB1, (const char*)K_lds + bc * SHM_K);
;         FSM(pA0, pA1, alA); SBAR();
;         SLOAD(SO, (j + SD) * KVBLK); SBAR();
;         PVX(bp * (int)SHM_V, pB0); PSMG(pB0, pB1, mnB, alB);
;         SWAIT(); SWRITE(bn, SE);
;         RESCX(alB); __syncthreads();
;         { const int t_ = bp; bp = bc; bc = bn; bn = t_; }
;         SBAR(); QKT(pA0, pA1, (const char*)K_lds + bc * SHM_K);
;         FSM(pB0, pB1, alB); SBAR();
;         if (SD == 1 || j + 3 < NT) SLOAD(SE, (j + 1 + SD) * KVBLK); SBAR();
;         PVX(bp * (int)SHM_V, pA0); PSMG(pA0, pA1, mnA, alA);
;         SWAIT(); SWRITE(bn, SO);
;         RESCX(alA); __syncthreads();
;         { const int t_ = bp; bp = bc; bc = bn; bn = t_; }
;     }
.Lf4_loop:
	s_mov_b32 s47, s35
	s_mov_b32 s35, s44
	s_lshl_b32 s49, s47, 14
	s_lshl_b32 s50, s44, 14
	v_add_u32_e32 v250, v252, v202
	v_add_u32_e32 v251, v252, v203
	v_add_u32_e32 v253, s50, v207
	ds_read_b128 v[216:219], v250 offset:53248
	ds_read_b128 v[220:223], v251 offset:53248
	ds_read_b128 v[136:139], v253
	ds_read_b128 v[140:143], v253 offset:16
	ds_read_b128 v[240:243], v253 offset:2560
	ds_read_b128 v[244:247], v253 offset:2576
	v_cvt_pk_bf8_f32 v128, v64, v65
	v_cvt_pk_bf8_f32 v129, v68, v69
	v_cvt_pk_bf8_f32 v130, v72, v73
	v_cvt_pk_bf8_f32 v131, v76, v77
	v_exp_f32_e32 v80, v80
	v_exp_f32_e32 v81, v81
	s_waitcnt lgkmcnt(6)
	v_mfma_scale_f32_32x32x64_f8f6f4 v[96:111], v[208:215], v[152:159], -4.0, v189, v190 op_sel_hi:[0,0,0]
	v_cvt_pk_bf8_f32 v128, v66, v67 op_sel:[0,0,1]
	v_cvt_pk_bf8_f32 v129, v70, v71 op_sel:[0,0,1]
	ds_read_b128 v[208:211], v253 offset:5120
	ds_read_b128 v[212:215], v253 offset:5136
	v_cvt_pk_bf8_f32 v130, v74, v75 op_sel:[0,0,1]
	v_cvt_pk_bf8_f32 v131, v78, v79 op_sel:[0,0,1]
	v_exp_f32_e32 v84, v84
	v_exp_f32_e32 v85, v85
	v_exp_f32_e32 v88, v88
	s_waitcnt lgkmcnt(6)
	v_mfma_scale_f32_32x32x64_f8f6f4 v[112:127], v[216:223], v[152:159], -4.0, v189, v190 op_sel_hi:[0,0,0]
	v_exp_f32_e32 v89, v89
	v_exp_f32_e32 v92, v92
	v_exp_f32_e32 v93, v93
	ds_read_b128 v[216:219], v253 offset:7680
	ds_read_b128 v[220:223], v253 offset:7696
	v_exp_f32_e32 v82, v82
	v_exp_f32_e32 v83, v83
	v_exp_f32_e32 v86, v86
	v_exp_f32_e32 v87, v87
	v_exp_f32_e32 v90, v90
	v_mfma_scale_f32_32x32x64_f8f6f4 v[96:111], v[224:231], v[144:151], v[96:111], v189, v190 op_sel_hi:[0,0,0]
	v_exp_f32_e32 v91, v91
	v_exp_f32_e32 v94, v94
	v_exp_f32_e32 v95, v95
	v_cvt_pk_bf8_f32 v132, v80, v81
	v_cvt_pk_bf8_f32 v133, v84, v85
	v_cvt_pk_bf8_f32 v134, v88, v89
	v_cvt_pk_bf8_f32 v135, v92, v93
	v_mfma_scale_f32_32x32x64_f8f6f4 v[112:127], v[232:239], v[144:151], v[112:127], v189, v190 op_sel_hi:[0,0,0]
	v_cvt_pk_bf8_f32 v132, v82, v83 op_sel:[0,0,1]
	v_cvt_pk_bf8_f32 v133, v86, v87 op_sel:[0,0,1]
	v_cvt_pk_bf8_f32 v134, v90, v91 op_sel:[0,0,1]
	v_cvt_pk_bf8_f32 v135, v94, v95 op_sel:[0,0,1]
	v_lshl_add_u64 v[186:187], s[28:29], 0, v[182:183]
	v_add_co_u32_e32 v250, vcc, s62, v186
	v_lshl_add_u64 v[184:185], s[28:29], 0, v[180:181]
	v_add_f32_e32 v248, v64, v65
	v_addc_co_u32_e32 v251, vcc, 0, v187, vcc
	v_add_co_u32_e32 v252, vcc, s63, v184
	v_add_f32_e32 v249, v80, v81
	v_add_f32_e32 v248, v66, v248
	v_addc_co_u32_e32 v253, vcc, 0, v185, vcc
	global_load_dwordx4 v[172:175], v[250:251], off
	global_load_dwordx4 v[168:171], v[252:253], off
	v_add_f32_e32 v249, v82, v249
	s_waitcnt lgkmcnt(6)
	v_mfma_f32_32x32x64_f8f6f4 v[0:15], v[128:135], v[136:143], v[0:15] cbsz:1
	s_lshl_b32 s44, s46, 14
	v_add_u32_e32 v250, s44, v199
	s_add_i32 s48, s44, 0
	v_add_u32_e32 v251, s48, v198
	v_add_u32_e32 v252, s48, v200
	s_waitcnt vmcnt(2)
	ds_write_b128 v250, v[164:167]
	ds_write_b64 v251, v[160:161] offset:49152
	ds_write_b64 v252, v[162:163] offset:49152
	v_add_f32_e32 v248, v67, v248
	v_add_f32_e32 v249, v83, v249
	v_add_f32_e32 v248, v68, v248
	v_add_f32_e32 v249, v84, v249
	v_add_f32_e32 v248, v69, v248
	v_add_f32_e32 v249, v85, v249
	v_add_f32_e32 v248, v70, v248
	v_add_f32_e32 v249, v86, v249
	v_add_f32_e32 v248, v71, v248
	v_add_f32_e32 v249, v87, v249
	v_add_f32_e32 v248, v72, v248
	v_add_f32_e32 v249, v88, v249
	s_waitcnt lgkmcnt(7)
	v_mfma_f32_32x32x64_f8f6f4 v[16:31], v[128:135], v[240:247], v[16:31] cbsz:1
	v_add_f32_e32 v248, v73, v248
	v_add_f32_e32 v249, v89, v249
	v_add_f32_e32 v248, v74, v248
	v_add_f32_e32 v249, v90, v249
	v_add_f32_e32 v248, v75, v248
	v_add_f32_e32 v249, v91, v249
	v_add_f32_e32 v248, v76, v248
	v_add_f32_e32 v249, v92, v249
	v_add_f32_e32 v248, v77, v248
	v_add_f32_e32 v249, v93, v249
	v_exp_f32_e32 v96, v96
	v_exp_f32_e32 v97, v97
	v_exp_f32_e32 v98, v98
	v_exp_f32_e32 v99, v99
	s_waitcnt lgkmcnt(0)
	s_barrier
; #define SBAR() __builtin_amdgcn_sched_barrier(0)
; #define SWAIT() do { if constexpr (FIXED) asm volatile("s_waitcnt vmcnt(2)" ::: "memory"); else if constexpr (SD == 2) asm volatile("s_waitcnt vmcnt(4)" ::: "memory"); else asm volatile("s_waitcnt vmcnt(0)" ::: "memory"); } while (0)
; #define FSM(P0, P1, AL) do { if constexpr (FIXED) finishSM8(P0, P1, l_reg, pa8); else finishSM(P0, P1, AL, l_reg, pa0, pa1, pa2, pa3); } while (0)
; #define PVX(VOFF, PE) do { if constexpr (FIXED) pv8<true>(o, (const char*)V_lds + (VOFF), pa8, r32, hi, PE); else pv_d0(o, vb0 + (VOFF), pa0, pa1, pa2, pa3); } while (0)
; #define PSMG(P0, P1, MN, AL) do { if constexpr (!FIXED) partialSM(P0, P1, m_reg, MN, AL); } while (0)
; #define RESCX(a) do { if constexpr (!FIXED) RESC(a); } while (0)
; #define QKT(P0, P1, KP) do { if constexpr (FIXED) qkt8(P0, P1, KP, q8, r32, hi); else qkt<false>(P0, P1, (const bf16_t*)(KP), qr, r32, hi, qinit); } while (0)
; template <bool FIXED> ...
;     ...
;     for (int j = 1; j + 1 < NT; j += 2) {
;         SBAR(); QKT(pB0, pB1, (const char*)K_lds + bc * SHM_K);
;         FSM(pA0, pA1, alA); SBAR();
;         SLOAD(SO, (j + SD) * KVBLK); SBAR();
;         PVX(bp * (int)SHM_V, pB0); PSMG(pB0, pB1, mnB, alB);
;         SWAIT(); SWRITE(bn, SE);
;         RESCX(alB); __syncthreads();
;         { const int t_ = bp; bp = bc; bc = bn; bn = t_; }
;         SBAR(); QKT(pA0, pA1, (const char*)K_lds + bc * SHM_K);
;         FSM(pB0, pB1, alB); SBAR();
;         if (SD == 1 || j + 3 < NT) SLOAD(SE, (j + 1 + SD) * KVBLK); SBAR();
;         PVX(bp * (int)SHM_V, pA0); PSMG(pA0, pA1, mnA, alA);
;         SWAIT(); SWRITE(bn, SO);
;         RESCX(alA); __syncthreads();
;         { const int t_ = bp; bp = bc; bc = bn; bn = t_; }
;     }
	v_add_u32_e32 v252, s48, v201
	v_add_u32_e32 v250, v252, v205
	v_add_u32_e32 v251, v252, v206
	ds_read_b128 v[224:227], v250 offset:49152
	ds_read_b128 v[228:231], v251 offset:49152
	ds_read_b128 v[232:235], v250 offset:53248
	ds_read_b128 v[236:239], v251 offset:53248
	v_mfma_f32_32x32x64_f8f6f4 v[32:47], v[128:135], v[208:215], v[32:47] cbsz:1
	v_add_u32_e32 v250, v252, v202
	v_add_u32_e32 v251, v252, v203
	v_add_f32_e32 v248, v78, v248
	v_add_f32_e32 v249, v94, v249
	ds_read_b128 v[208:211], v250 offset:49152
	ds_read_b128 v[212:215], v251 offset:49152
	v_exp_f32_e32 v100, v100
	v_exp_f32_e32 v101, v101
	v_exp_f32_e32 v102, v102
	v_exp_f32_e32 v103, v103
	v_exp_f32_e32 v104, v104
	v_exp_f32_e32 v105, v105
	v_mfma_f32_32x32x64_f8f6f4 v[48:63], v[128:135], v[216:223], v[48:63] cbsz:1
	v_add_f32_e32 v248, v79, v248
	v_add_f32_e32 v249, v95, v249
	v_add_f32_e32 v178, v178, v248
	v_add_f32_e32 v178, v178, v249
	v_exp_f32_e32 v106, v106
	v_exp_f32_e32 v107, v107
	v_exp_f32_e32 v108, v108
	v_exp_f32_e32 v109, v109
	v_exp_f32_e32 v110, v110
	v_exp_f32_e32 v111, v111
	v_add_u32_e32 v250, v252, v202
	v_add_u32_e32 v251, v252, v203
	v_add_u32_e32 v253, s49, v207
	s_add_i32 s49, s50, 0
	ds_read_b128 v[216:219], v250 offset:53248
	ds_read_b128 v[220:223], v251 offset:53248
	ds_read_b128 v[136:139], v253
	ds_read_b128 v[140:143], v253 offset:16
	ds_read_b128 v[240:243], v253 offset:2560
	ds_read_b128 v[244:247], v253 offset:2576
	v_cvt_pk_bf8_f32 v128, v96, v97
	v_cvt_pk_bf8_f32 v129, v100, v101
	v_cvt_pk_bf8_f32 v130, v104, v105
	v_cvt_pk_bf8_f32 v131, v108, v109
	v_exp_f32_e32 v112, v112
	v_exp_f32_e32 v113, v113
	s_waitcnt lgkmcnt(6)
	v_mfma_scale_f32_32x32x64_f8f6f4 v[64:79], v[208:215], v[152:159], -4.0, v189, v190 op_sel_hi:[0,0,0]
	v_cvt_pk_bf8_f32 v128, v98, v99 op_sel:[0,0,1]
	v_cvt_pk_bf8_f32 v129, v102, v103 op_sel:[0,0,1]
	ds_read_b128 v[208:211], v253 offset:5120
	ds_read_b128 v[212:215], v253 offset:5136
	v_cvt_pk_bf8_f32 v130, v106, v107 op_sel:[0,0,1]
	v_cvt_pk_bf8_f32 v131, v110, v111 op_sel:[0,0,1]
	v_exp_f32_e32 v116, v116
	v_exp_f32_e32 v117, v117
	v_exp_f32_e32 v120, v120
	s_waitcnt lgkmcnt(6)
	v_mfma_scale_f32_32x32x64_f8f6f4 v[80:95], v[216:223], v[152:159], -4.0, v189, v190 op_sel_hi:[0,0,0]
	v_exp_f32_e32 v121, v121
	v_exp_f32_e32 v124, v124
	v_exp_f32_e32 v125, v125
	ds_read_b128 v[216:219], v253 offset:7680
	ds_read_b128 v[220:223], v253 offset:7696
	v_exp_f32_e32 v114, v114
	v_exp_f32_e32 v115, v115
	v_exp_f32_e32 v118, v118
	v_exp_f32_e32 v119, v119
	v_exp_f32_e32 v122, v122
	v_mfma_scale_f32_32x32x64_f8f6f4 v[64:79], v[224:231], v[144:151], v[64:79], v189, v190 op_sel_hi:[0,0,0]
	v_exp_f32_e32 v123, v123
	v_exp_f32_e32 v126, v126
	v_exp_f32_e32 v127, v127
	v_cvt_pk_bf8_f32 v132, v112, v113
	v_cvt_pk_bf8_f32 v133, v116, v117
	v_cvt_pk_bf8_f32 v134, v120, v121
	v_cvt_pk_bf8_f32 v135, v124, v125
	v_mfma_scale_f32_32x32x64_f8f6f4 v[80:95], v[232:239], v[144:151], v[80:95], v189, v190 op_sel_hi:[0,0,0]
	v_cvt_pk_bf8_f32 v132, v114, v115 op_sel:[0,0,1]
	v_cvt_pk_bf8_f32 v133, v118, v119 op_sel:[0,0,1]
	v_cvt_pk_bf8_f32 v134, v122, v123 op_sel:[0,0,1]
	v_cvt_pk_bf8_f32 v135, v126, v127 op_sel:[0,0,1]
	s_cmp_ge_u32 s3, s69
	s_cbranch_scc1 .Lf4_skip
	v_add_co_u32_e32 v160, vcc, 0x49730000, v186
	v_add_f32_e32 v248, v96, v97
	v_add_f32_e32 v249, v112, v113
	v_addc_co_u32_e32 v161, vcc, 0, v187, vcc
	v_add_co_u32_e32 v162, vcc, 0x48b30000, v184
	v_add_f32_e32 v248, v98, v248
	v_add_f32_e32 v249, v114, v249
	v_addc_co_u32_e32 v163, vcc, 0, v185, vcc
	global_load_dwordx4 v[164:167], v[160:161], off
	s_nop 0
	global_load_dwordx4 v[160:163], v[162:163], off
	s_branch .Lf4_sedone

; #define SBAR() __builtin_amdgcn_sched_barrier(0)
; #define SWAIT() do { if constexpr (FIXED) asm volatile("s_waitcnt vmcnt(2)" ::: "memory"); else if constexpr (SD == 2) asm volatile("s_waitcnt vmcnt(4)" ::: "memory"); else asm volatile("s_waitcnt vmcnt(0)" ::: "memory"); } while (0)
; #define FSM(P0, P1, AL) do { if constexpr (FIXED) finishSM8(P0, P1, l_reg, pa8); else finishSM(P0, P1, AL, l_reg, pa0, pa1, pa2, pa3); } while (0)
; #define PVX(VOFF, PE) do { if constexpr (FIXED) pv8<true>(o, (const char*)V_lds + (VOFF), pa8, r32, hi, PE); else pv_d0(o, vb0 + (VOFF), pa0, pa1, pa2, pa3); } while (0)
; #define PSMG(P0, P1, MN, AL) do { if constexpr (!FIXED) partialSM(P0, P1, m_reg, MN, AL); } while (0)
; #define RESCX(a) do { if constexpr (!FIXED) RESC(a); } while (0)
; #define QKT(P0, P1, KP) do { if constexpr (FIXED) qkt8(P0, P1, KP, q8, r32, hi); else qkt<false>(P0, P1, (const bf16_t*)(KP), qr, r32, hi, qinit); } while (0)
; template <bool FIXED> ...
;     ...
;     for (int j = 1; j + 1 < NT; j += 2) {
;         SBAR(); QKT(pB0, pB1, (const char*)K_lds + bc * SHM_K);
;         FSM(pA0, pA1, alA); SBAR();
;         SLOAD(SO, (j + SD) * KVBLK); SBAR();
;         PVX(bp * (int)SHM_V, pB0); PSMG(pB0, pB1, mnB, alB);
;         SWAIT(); SWRITE(bn, SE);
;         RESCX(alB); __syncthreads();
;         { const int t_ = bp; bp = bc; bc = bn; bn = t_; }
;         SBAR(); QKT(pA0, pA1, (const char*)K_lds + bc * SHM_K);
;         FSM(pB0, pB1, alB); SBAR();
;         if (SD == 1 || j + 3 < NT) SLOAD(SE, (j + 1 + SD) * KVBLK); SBAR();
;         PVX(bp * (int)SHM_V, pA0); PSMG(pA0, pA1, mnA, alA);
;         SWAIT(); SWRITE(bn, SO);
;         RESCX(alA); __syncthreads();
;         { const int t_ = bp; bp = bc; bc = bn; bn = t_; }
;     }
.Lf4_sedone:
	s_waitcnt lgkmcnt(6)
	v_mfma_f32_32x32x64_f8f6f4 v[0:15], v[128:135], v[136:143], v[0:15] cbsz:1
	v_add_u32_e32 v250, s50, v199
	v_add_u32_e32 v251, s49, v198
	v_add_u32_e32 v252, s49, v200
	s_cmp_ge_u32 s3, s69
	s_cbranch_scc1 .Lf4_lastw
	s_waitcnt vmcnt(2)
.Lf4_wr:
	ds_write_b128 v250, v[172:175]
	ds_write_b64 v251, v[168:169] offset:49152
	ds_write_b64 v252, v[170:171] offset:49152
	v_add_f32_e32 v248, v99, v248
	v_add_f32_e32 v249, v115, v249
	v_add_f32_e32 v248, v100, v248
	v_add_f32_e32 v249, v116, v249
	v_add_f32_e32 v248, v101, v248
	v_add_f32_e32 v249, v117, v249
	v_add_f32_e32 v248, v102, v248
	v_add_f32_e32 v249, v118, v249
	v_add_f32_e32 v248, v103, v248
	v_add_f32_e32 v249, v119, v249
	v_add_f32_e32 v248, v104, v248
	v_add_f32_e32 v249, v120, v249
	s_waitcnt lgkmcnt(7)
	v_mfma_f32_32x32x64_f8f6f4 v[16:31], v[128:135], v[240:247], v[16:31] cbsz:1
	v_add_f32_e32 v248, v105, v248
	v_add_f32_e32 v249, v121, v249
	v_add_f32_e32 v248, v106, v248
	v_add_f32_e32 v249, v122, v249
	v_add_f32_e32 v248, v107, v248
	v_add_f32_e32 v249, v123, v249
	v_add_f32_e32 v248, v108, v248
	v_add_f32_e32 v249, v124, v249
	v_add_f32_e32 v248, v109, v248
	v_add_f32_e32 v249, v125, v249
	v_exp_f32_e32 v64, v64
	v_exp_f32_e32 v65, v65
	v_exp_f32_e32 v66, v66
	v_exp_f32_e32 v67, v67
	s_waitcnt lgkmcnt(0)
	s_barrier
	s_lshl_b32 s50, s35, 14
	v_add_u32_e32 v252, s50, v201
	v_add_u32_e32 v250, v252, v205
	v_add_u32_e32 v251, v252, v206
	ds_read_b128 v[224:227], v250 offset:49152
	ds_read_b128 v[228:231], v251 offset:49152
	ds_read_b128 v[232:235], v250 offset:53248
	ds_read_b128 v[236:239], v251 offset:53248
	v_mfma_f32_32x32x64_f8f6f4 v[32:47], v[128:135], v[208:215], v[32:47] cbsz:1
	v_add_u32_e32 v250, v252, v202
	v_add_u32_e32 v251, v252, v203
	v_add_f32_e32 v248, v110, v248
	v_add_f32_e32 v249, v126, v249
	ds_read_b128 v[208:211], v250 offset:49152
	ds_read_b128 v[212:215], v251 offset:49152
	v_exp_f32_e32 v68, v68
	v_exp_f32_e32 v69, v69
	v_exp_f32_e32 v70, v70
	v_exp_f32_e32 v71, v71
	v_exp_f32_e32 v72, v72
	v_exp_f32_e32 v73, v73
	v_mfma_f32_32x32x64_f8f6f4 v[48:63], v[128:135], v[216:223], v[48:63] cbsz:1
	v_add_f32_e32 v248, v111, v248
	v_add_f32_e32 v249, v127, v249
	v_add_f32_e32 v178, v178, v248
	v_add_f32_e32 v178, v178, v249
	v_exp_f32_e32 v74, v74
	v_exp_f32_e32 v75, v75
	v_exp_f32_e32 v76, v76
	v_exp_f32_e32 v77, v77
	v_exp_f32_e32 v78, v78
	v_exp_f32_e32 v79, v79
	v_lshl_add_u64 v[180:181], v[180:181], 0, s[22:23]
	v_lshl_add_u64 v[182:183], v[182:183], 0, s[22:23]
	s_cmp_ge_u32 s3, s69
	s_cbranch_scc1 .LBB0_1031
	s_add_i32 s3, s3, 2
	s_mov_b32 s44, s46
	s_mov_b32 s46, s47
	s_branch .Lf4_loop
